# all small passing edits stacked: store-aware counted waits (6c), conflict-free LDS pitch (6a), final-norm gain hoist, static priority for waves 4-7 in recurrence phases
# speedup vs baseline: 1.0100x; 1.0016x over previous
; template <int MODE>
; __device__ __forceinline__ void gdn_job(const Params& P, float* lw, int head, int rb, int seg) {
;     float* sk = lw; float* sq = lw + 1024; float* sv = lw + 2048; float* sal = lw + 2304; float* sbe = lw + 2312;
;     bf16_t* proj = (bf16_t*)(P.ws + WS_BIG);
;     const bf16_t* gp = (const bf16_t*)(P.ws + WS_GDNP); const float* gbeta = (const float*)(P.ws + WS_GBETA); const float* gg = (const float*)(P.ws + WS_GG);
;     const int lane = threadIdx.x & 63, jg = lane & 7, ig = lane >> 3, qh = head >> 1;
;     const int ltt = lane >> 3, lc16 = (lane & 7) * 16, lc4 = (lane & 7) * 4;
;     const int row0 = rb * 32 + ig * 4;
;     f32x2 S[4][8];
;     if constexpr (MODE == 2) {
;         const float* sp = (const float*)((const unsigned char*)P.out + 96 * MiB) + ((size_t)(head * NSEG + seg) * 128 + row0) * 128 + jg * 16;
; #pragma unroll
;         for (int ri = 0; ri < 4; ++ri)
; #pragma unroll
;             for (int q4 = 0; q4 < 4; ++q4) { const f32x4 a = *(const f32x4*)(sp + ri * 128 + q4 * 4); S[ri][2 * q4] = (f32x2){a.x, a.y}; S[ri][2 * q4 + 1] = (f32x2){a.z, a.w}; }
;     } else {
; #pragma unroll
;         for (int ri = 0; ri < 4; ++ri)
; #pragma unroll
;             for (int jj = 0; jj < 8; ++jj) { S[ri][jj] = (f32x2){0.f, 0.f}; if (MODE == 0) { if (row0 + ri == jg * 16 + 2 * jj) S[ri][jj].x = 1.f; if (row0 + ri == jg * 16 + 2 * jj + 1) S[ri][jj].y = 1.f; } }
;     }
;     u32x4 g_k0, g_k1, g_q0, g_q1; u32x2 g_v; float g_al = 0.f, g_be = 0.f;
;     const int tbase = seg * SEGLEN;
; __global__ void __launch_bounds__(512, 2) fwd_megakernel(Params P) {
;     ...
;         const int wid = threadIdx.x >> 6, gw = wg * 8 + wid, ngw = nwg * 8;
;         float* lw = (float*)(smem + wid * WAVE_LDS);
;         for (int j = gw; j < 2048; j += ngw) gdn_job<0>(P, lw, ((j >> 9) << 1) | ((j >> 2) & 1), j & 3, (j >> 3) & 63);
.Lprio_done0:
	s_cmp_lg_u32 s101, 0
	s_and_saveexec_b64 s[10:11], s[8:9]
	s_cbranch_execz .LBB0_532
	s_add_u32 s12, s26, 0x4000000
	s_addc_u32 s13, s27, 0
	s_add_u32 s14, s26, 0x4080000
	v_and_b32_e32 v106, 0x70, v164
	s_addc_u32 s15, s27, 0
	v_mov_b32_e32 v113, 0
	v_lshl_add_u32 v139, v106, 2, v136
	v_and_b32_e32 v220, 64, v106
	v_lshrrev_b32_e32 v220, 2, v220
	v_add_u32_e32 v139, v139, v220
	s_add_u32 s18, s24, 0x4000000
	v_lshlrev_b32_e32 v112, 1, v106
	v_add_u32_e32 v2, 0, v133
	v_and_b32_e32 v138, 28, v137
	v_or_b32_e32 v107, 4, v106
	v_or_b32_e32 v118, 8, v106
	v_or_b32_e32 v119, 12, v106
	v_cmp_gt_u32_e32 vcc, 8, v160
	v_mul_u32_u24_e32 v140, 0x210, v111
	v_add_u32_e32 v140, v140, v139
	v_lshl_add_u32 v141, v160, 2, v136
	s_addc_u32 s19, s25, 0
	v_lshl_add_u64 v[108:109], s[26:27], 0, v[112:113]
	v_add_u32_e32 v142, 0x2400, v2
	s_mov_b64 s[56:57], 0
	v_lshlrev_b32_e32 v114, 1, v106
	v_mov_b32_e32 v115, v113
	s_movk_i32 s40, 0x60
	s_movk_i32 s41, 0x7ff
	v_mov_b32_e32 v120, v162
	s_branch .LBB0_484
